# LRU pass-1: next work-queue index pulled early in the current item (atomic latency hidden), on top of the parameter-load hoist
# speedup vs baseline: 1.0024x; 1.0024x over previous
; #define LAS __attribute__((address_space(3)))
; #define GAS __attribute__((address_space(1)))
; __device__ __forceinline__ int queue_pull(unsigned* q, int lane) { unsigned nx = 0; if (lane == 0) nx = __hip_atomic_fetch_add(q, 1u, __ATOMIC_RELAXED, __HIP_MEMORY_SCOPE_AGENT); return 256 + (int)__builtin_amdgcn_readfirstlane(nx); }
; __device__ __forceinline__ int lru_pass1(const Params& P, int l, LAS unsigned char* lds, unsigned* qw) {
;     int tid = threadIdx.x; asm volatile("" : "+v"(tid)); const int lane = tid & 63, fr = lane & 15, fq = lane >> 4;
;     const GAS bf16_t* Z = (const GAS bf16_t*)(P.ws + OFF_Z);
;     const GAS bf16_t* WGT = (const GAS bf16_t*)(P.ws + OFF_WGT + l * SZ_WGT1); GAS float* AGG = (GAS float*)(P.ws + OFF_AGG); GAS unsigned* AB = (GAS unsigned*)(P.ws + OFF_AB);
;     LAS unsigned short* xcS = (LAS unsigned short*)(lds + (tid >> 6) * 9216);
;     LAS unsigned short* xaS = (LAS unsigned short*)(lds + 8 * 9216 + (tid >> 6) * 8704);
;     const GAS float* SP8 = (const GAS float*)(P.ws + OFF_SP8);
;     const int wslot = tid >> 6;
;     const int xq = blockIdx.x & 7, jq = blockIdx.x >> 3;
;     int local = jq >= 16 ? (jq - 16) * 8 + wslot : 128 + jq * 8 + wslot;
;     for (;;) {
;         if (local >= 544) break;
;         const int wi = xq * 544 + local;
;         const int it = wi >> 3, h = wi & 7;
;         int b, j, q, Ls, r0seq;
;         if (it < 512) { b = it >> 6; j = it & 63; q = 4 + j; Ls = 4096; r0seq = b * 4096; } else { const int t2 = it - 512; b = t2 >> 2; j = t2 & 3; q = j; Ls = 256; r0seq = TL + b * 256; }
;         const int n0 = j * 64, r0 = r0seq + n0;
;     ...
;         asm volatile("s_waitcnt lgkmcnt(0)" ::: "memory");
;         local = queue_pull(qw, lane);
.LBB0_545:
	s_or_b64 exec, exec, s[8:9]
	v_mov_b32_e32 v0, v168
	v_readlane_b32 s0, v252, 32
	v_ashrrev_i32_e32 v1, 6, v0
	s_nop 0
	v_add_u32_e32 v32, s0, v1
	s_movk_i32 s0, 0x220
	v_cmp_gt_i32_e32 vcc, s0, v32
	s_and_saveexec_b64 s[48:49], vcc
	s_cbranch_execz .LBB0_629
	s_movk_i32 s0, 0x2400
	v_mul_lo_u32 v2, v1, s0
	s_movk_i32 s0, 0x2200
	v_and_b32_e32 v184, 63, v0
	v_mul_lo_u32 v1, v1, s0
	s_add_i32 s0, 0, 0x12000
	v_lshlrev_b32_e32 v4, 4, v0
	s_waitcnt lgkmcnt(0)
	v_add_u32_e32 v3, 0, v2
	v_add_u32_e32 v1, s0, v1
	v_and_b32_e32 v128, 0x70, v4
	v_lshlrev_b32_e32 v6, 1, v184
	v_add_u32_e32 v5, v1, v128
	v_add_u32_e32 v186, v1, v6
	v_add_u32_e32 v187, v3, v6
	v_or_b32_e32 v6, 64, v184
	v_and_b32_e32 v4, 0x380, v4
	v_add_u32_e32 v197, v5, v4
	v_lshlrev_b32_e32 v4, 4, v6
	v_or_b32_e32 v7, 0x80, v184
	v_and_b32_e32 v4, 0x780, v4
	v_add_u32_e32 v198, v5, v4
	v_lshlrev_b32_e32 v4, 4, v7
	v_or_b32_e32 v8, 0xc0, v184
	v_and_b32_e32 v4, 0xb80, v4
	v_add_u32_e32 v199, v5, v4
	v_lshlrev_b32_e32 v4, 4, v8
	v_or_b32_e32 v9, 0x100, v184
	v_and_b32_e32 v4, 0xf80, v4
	v_readlane_b32 s0, v253, 25
	v_add_u32_e32 v200, v5, v4
	v_lshlrev_b32_e32 v4, 4, v9
	v_readlane_b32 s1, v253, 26
	v_or_b32_e32 v10, 0x140, v184
	v_and_b32_e32 v4, 0x1380, v4
	v_lshl_add_u64 v[96:97], s[0:1], 0, v[128:129]
	v_or_b32_e32 v13, 0x200, v184
	v_add_u32_e32 v201, v5, v4
	v_lshlrev_b32_e32 v4, 4, v10
	s_movk_i32 s0, 0x218
	v_and_b32_e32 v185, 15, v0
	v_and_b32_e32 v1, 3, v0
	v_and_b32_e32 v98, 48, v0
	v_bfe_u32 v188, v0, 3, 3
	v_or_b32_e32 v11, 0x180, v184
	v_and_b32_e32 v4, 0x1780, v4
	v_cmp_gt_u32_e64 s[42:43], s0, v13
	v_lshlrev_b32_e32 v0, 2, v0
	s_movk_i32 s0, 0x90
	v_add_u32_e32 v202, v5, v4
	v_lshlrev_b32_e32 v4, 4, v11
	v_and_or_b32 v0, v0, 48, v1
	v_mad_u32_u24 v1, v98, s0, v2
	v_readlane_b32 s0, v255, 23
	v_or_b32_e32 v12, 0x1c0, v184
	v_and_b32_e32 v4, 0x1b80, v4
	v_add_u32_e32 v208, s0, v185
	v_readlane_b32 s0, v255, 10
	v_add_u32_e32 v203, v5, v4
	v_lshlrev_b32_e32 v4, 4, v12
	v_mov_b32_e32 v99, v129
	v_readlane_b32 s1, v255, 11
	v_and_b32_e32 v4, 0x1f80, v4
	v_lshlrev_b32_e32 v206, 1, v185
	v_lshl_add_u64 v[100:101], s[0:1], 0, v[98:99]
	v_readlane_b32 s0, v255, 26
	v_add_u32_e32 v204, v5, v4
	v_lshlrev_b32_e32 v4, 4, v13
	v_or_b32_e32 v1, v1, v206
	v_add_u32_e32 v99, s0, v185
	v_readlane_b32 s0, v255, 22
	v_add_u32_e32 v3, v3, v98
	v_lshrrev_b32_e32 v14, 3, v13
	v_and_b32_e32 v4, 0x2380, v4
	v_mul_u32_u24_e32 v0, 0x90, v0
	v_add_u32_e32 v207, 0, v1
	v_lshlrev_b32_e32 v1, 6, v185
	v_add_u32_e32 v209, s0, v185
	v_readlane_b32 s0, v255, 24
	v_cmp_gt_u32_e64 s[38:39], 16, v184
	v_cmp_eq_u32_e64 s[40:41], 0, v184
	v_lshrrev_b32_e32 v189, 3, v6
	v_lshrrev_b32_e32 v190, 3, v7
	v_lshrrev_b32_e32 v191, 3, v8
	v_lshrrev_b32_e32 v192, 3, v9
	v_lshrrev_b32_e32 v193, 3, v10
	v_lshrrev_b32_e32 v194, 3, v11
	v_lshrrev_b32_e32 v195, 3, v12
	v_min_u32_e32 v196, 0x42, v14
	v_add_u32_e32 v205, v5, v4
	v_add_u32_e32 v210, s0, v185
	v_add_u32_e32 v211, v3, v0
	v_lshlrev_b32_e32 v212, 1, v1
	v_readlane_b32 s1, v255, 25
	s_branch .LBB0_549
.LBB0_548:
	s_or_b64 exec, exec, s[8:9]
	v_readfirstlane_b32 s1, v0
	s_add_i32 s0, s1, 0x100
	s_cmpk_gt_i32 s1, 0x11f
	v_mov_b32_e32 v32, s0
	s_cbranch_scc1 .LBB0_628

; __device__ __forceinline__ float bf2f(unsigned short b) { return __uint_as_float(((unsigned)b) << 16); }
; __device__ __forceinline__ int lru_pass1(const Params& P, int l, LAS unsigned char* lds, unsigned* qw) {
;     ...
;             const int c = h * 64 + lane; const float* cw = P.conv_w + l * 4 * 512 + c; const float w0 = cw[0], w1 = cw[512], w2 = cw[1024], w3 = cw[1536], cb = P.conv_b[l * 512 + c];
;             float xv[67];
; #pragma unroll
;             for (int i = 0; i < 67; ++i) { const int n = n0 - 2 + i; xv[i] = bf2f(xaS[i * 64 + lane]) * ((n >= 0 && n < Ls) ? 1.0f : 0.0f); }
; #pragma unroll
;             for (int p = 0; p < 64; p += 2) { const float xc0 = cb + w0 * xv[p] + w1 * xv[p + 1] + w2 * xv[p + 2] + w3 * xv[p + 3], xc1 = cb + w0 * xv[p + 1] + w1 * xv[p + 2] + w2 * xv[p + 3] + w3 * xv[p + 4];
.LBB0_555:
	s_or_b64 exec, exec, s[8:9]
	v_or_b32_e32 v4, v33, v184
	v_readlane_b32 s0, v254, 54
	v_lshlrev_b32_e32 v128, 2, v4
	v_readlane_b32 s1, v254, 55
	s_waitcnt lgkmcnt(0)
	s_nop 4
	global_load_dword v0, v128, s[0:1]
	global_load_dword v1, v128, s[0:1] offset:2048
	s_waitcnt vmcnt(2)
	v_lshl_add_u64 v[2:3], s[0:1], 0, v[128:129]
	v_add_co_u32_e32 v8, vcc, 0x1000, v2
	v_readlane_b32 s0, v254, 52
	s_nop 0
	v_addc_co_u32_e32 v9, vcc, 0, v3, vcc
	v_or_b32_e32 v128, s0, v4
	global_load_dword v3, v[8:9], off
	global_load_dword v2, v[8:9], off offset:2048
	v_lshl_add_u64 v[8:9], v[128:129], 2, s[52:53]
	global_load_dword v4, v[8:9], off
	ds_read_u16 v7, v186
	ds_read_u16 v8, v186 offset:128
	ds_read_u16 v9, v186 offset:256
	ds_read_u16 v10, v186 offset:384
	ds_read_u16 v11, v186 offset:512
	ds_read_u16 v13, v186 offset:640
	ds_read_u16 v15, v186 offset:768
	ds_read_u16 v17, v186 offset:896
	v_cmp_lt_u32_e32 vcc, v6, v5
	s_waitcnt lgkmcnt(7)
	v_lshlrev_b32_e32 v7, 16, v7
	v_add3_u32 v36, v36, v98, v37
	v_cndmask_b32_e64 v6, 0, 1.0, vcc
	v_mul_f32_e32 v16, v6, v7
	v_add_u32_e32 v6, -1, v37
	v_cmp_lt_u32_e32 vcc, v6, v5
	s_waitcnt lgkmcnt(6)
	v_lshlrev_b32_e32 v7, 16, v8
	s_movk_i32 s0, 0x44
	v_cndmask_b32_e64 v6, 0, 1.0, vcc
	v_cmp_lt_u32_e32 vcc, v37, v5
	v_mul_f32_e32 v14, v6, v7
	s_waitcnt lgkmcnt(5)
	v_lshlrev_b32_e32 v6, 16, v9
	v_cndmask_b32_e64 v7, 0, 1.0, vcc
	v_mul_f32_e32 v12, v7, v6
	v_or_b32_e32 v6, 1, v37
	v_cmp_lt_u32_e32 vcc, v6, v5
	s_waitcnt lgkmcnt(4)
	v_lshlrev_b32_e32 v7, 16, v10
	v_mul_lo_u32 v34, v34, s0
	v_cndmask_b32_e64 v6, 0, 1.0, vcc
	v_mul_f32_e32 v10, v6, v7
	v_or_b32_e32 v6, 2, v37
	v_cmp_lt_u32_e32 vcc, v6, v5
	s_waitcnt lgkmcnt(3)
	v_lshlrev_b32_e32 v7, 16, v11
	s_waitcnt lgkmcnt(0)
	v_lshlrev_b32_e32 v11, 16, v17
	v_cndmask_b32_e64 v6, 0, 1.0, vcc
	v_mul_f32_e32 v9, v6, v7
	v_or_b32_e32 v6, 3, v37
	v_cmp_lt_u32_e32 vcc, v6, v5
	v_lshlrev_b32_e32 v7, 16, v13
	s_mov_b64 s[0:1], 0x400
	v_cndmask_b32_e64 v6, 0, 1.0, vcc
	v_mul_f32_e32 v8, v6, v7
	v_or_b32_e32 v6, 4, v37
	v_cmp_lt_u32_e32 vcc, v6, v5
	v_lshlrev_b32_e32 v7, 16, v15
	ds_read_u16 v13, v186 offset:1024
	ds_read_u16 v15, v186 offset:1152
	ds_read_u16 v17, v186 offset:1280
	ds_read_u16 v18, v186 offset:1408
	ds_read_u16 v19, v186 offset:1536
	ds_read_u16 v21, v186 offset:1664
	ds_read_u16 v23, v186 offset:1792
	ds_read_u16 v25, v186 offset:1920
	v_cndmask_b32_e64 v6, 0, 1.0, vcc
	v_mul_f32_e32 v7, v6, v7
	v_or_b32_e32 v6, 5, v37
	v_cmp_lt_u32_e32 vcc, v6, v5
	s_waitcnt lgkmcnt(7)
	v_lshlrev_b32_e32 v13, 16, v13
	v_add_lshl_u32 v34, v34, v35, 1
	v_cndmask_b32_e64 v6, 0, 1.0, vcc
	v_mul_f32_e32 v6, v6, v11
	v_or_b32_e32 v11, 6, v37
	v_cmp_lt_u32_e32 vcc, v11, v5
	v_ashrrev_i32_e32 v35, 31, v34
	v_lshlrev_b64 v[102:103], 12, v[34:35]
	v_cndmask_b32_e64 v11, 0, 1.0, vcc
	v_mul_f32_e32 v24, v11, v13
	v_or_b32_e32 v11, 7, v37
	v_cmp_lt_u32_e32 vcc, v11, v5
	s_waitcnt lgkmcnt(6)
	v_lshlrev_b32_e32 v13, 16, v15
	v_and_b32_e32 v32, 7, v32
	v_cndmask_b32_e64 v11, 0, 1.0, vcc
	v_mul_f32_e32 v22, v11, v13
	v_or_b32_e32 v11, 8, v37
	v_cmp_lt_u32_e32 vcc, v11, v5
	s_waitcnt lgkmcnt(5)
	v_lshlrev_b32_e32 v13, 16, v17
	v_add_lshl_u32 v34, v208, v33, 2
	v_cndmask_b32_e64 v11, 0, 1.0, vcc
	v_mul_f32_e32 v20, v11, v13
	v_or_b32_e32 v11, 9, v37
	v_cmp_lt_u32_e32 vcc, v11, v5
	s_waitcnt lgkmcnt(4)
	v_lshlrev_b32_e32 v13, 16, v18
	v_mov_b32_e32 v35, v129
	v_cndmask_b32_e64 v11, 0, 1.0, vcc
	v_mul_f32_e32 v18, v11, v13
	v_or_b32_e32 v11, 10, v37
	v_cmp_lt_u32_e32 vcc, v11, v5
	s_waitcnt lgkmcnt(3)
	v_lshlrev_b32_e32 v13, 16, v19
	s_waitcnt lgkmcnt(0)
	v_lshlrev_b32_e32 v19, 16, v25
	v_cndmask_b32_e64 v11, 0, 1.0, vcc
	v_mul_f32_e32 v17, v11, v13
	v_or_b32_e32 v11, 11, v37
	v_cmp_lt_u32_e32 vcc, v11, v5
	v_lshlrev_b32_e32 v13, 16, v21
	s_waitcnt vmcnt(0)
	v_readlane_b32 s100, v254, 50
	v_readlane_b32 s101, v254, 51
	v_mov_b32_e32 v233, 1
	s_mov_b64 exec, 1
	s_nop 4
	global_atomic_add v232, v129, v233, s[100:101] sc0
	s_mov_b64 exec, -1
	s_nop 1
	v_fma_f32 v16, v0, v16, v4
	v_cndmask_b32_e64 v11, 0, 1.0, vcc
	v_mul_f32_e32 v15, v11, v13
	v_or_b32_e32 v11, 12, v37
	v_cmp_lt_u32_e32 vcc, v11, v5
	v_lshlrev_b32_e32 v13, 16, v23
	ds_read_u16 v21, v186 offset:2048
	ds_read_u16 v23, v186 offset:2176
	ds_read_u16 v25, v186 offset:2304
	ds_read_u16 v26, v186 offset:2432
	ds_read_u16 v27, v186 offset:2560
	ds_read_u16 v29, v186 offset:2688
	ds_read_u16 v31, v186 offset:2816
	ds_read_u16 v39, v186 offset:2944
	v_cndmask_b32_e64 v11, 0, 1.0, vcc
	v_mul_f32_e32 v13, v11, v13
	v_or_b32_e32 v11, 13, v37
	v_cmp_lt_u32_e32 vcc, v11, v5
	s_waitcnt lgkmcnt(7)
	v_lshlrev_b32_e32 v21, 16, v21
	v_fmac_f32_e32 v16, v1, v14
	v_cndmask_b32_e64 v11, 0, 1.0, vcc
	v_mul_f32_e32 v11, v11, v19
	v_or_b32_e32 v19, 14, v37
	v_cmp_lt_u32_e32 vcc, v19, v5
	v_fma_f32 v14, v0, v14, v4
	v_fmac_f32_e32 v16, v3, v12
	v_cndmask_b32_e64 v19, 0, 1.0, vcc
	v_mul_f32_e32 v38, v19, v21
	v_or_b32_e32 v19, 15, v37
	v_cmp_lt_u32_e32 vcc, v19, v5
	s_waitcnt lgkmcnt(6)
	v_lshlrev_b32_e32 v21, 16, v23
	v_fmac_f32_e32 v14, v1, v12
	v_cndmask_b32_e64 v19, 0, 1.0, vcc
	v_mul_f32_e32 v30, v19, v21
	v_or_b32_e32 v19, 16, v37
	v_cmp_lt_u32_e32 vcc, v19, v5
	s_waitcnt lgkmcnt(5)
	v_lshlrev_b32_e32 v21, 16, v25
	v_fma_f32 v12, v0, v12, v4
	v_cndmask_b32_e64 v19, 0, 1.0, vcc
	v_mul_f32_e32 v28, v19, v21
	v_or_b32_e32 v19, 17, v37
	v_cmp_lt_u32_e32 vcc, v19, v5
	s_waitcnt lgkmcnt(4)
	v_lshlrev_b32_e32 v21, 16, v26
	v_fmac_f32_e32 v16, v2, v10
	v_cndmask_b32_e64 v19, 0, 1.0, vcc
	v_mul_f32_e32 v26, v19, v21
	v_or_b32_e32 v19, 18, v37
	v_cmp_lt_u32_e32 vcc, v19, v5
	s_waitcnt lgkmcnt(3)
	v_lshlrev_b32_e32 v21, 16, v27
	s_waitcnt lgkmcnt(0)
; __device__ __forceinline__ float bf2f(unsigned short b) { return __uint_as_float(((unsigned)b) << 16); }
; __device__ __forceinline__ int lru_pass1(const Params& P, int l, LAS unsigned char* lds, unsigned* qw) {
;     ...
;             for (int i = 0; i < 67; ++i) { const int n = n0 - 2 + i; xv[i] = bf2f(xaS[i * 64 + lane]) * ((n >= 0 && n < Ls) ? 1.0f : 0.0f); }
; #pragma unroll
;             for (int p = 0; p < 64; p += 2) { const float xc0 = cb + w0 * xv[p] + w1 * xv[p + 1] + w2 * xv[p + 2] + w3 * xv[p + 3], xc1 = cb + w0 * xv[p + 1] + w1 * xv[p + 2] + w2 * xv[p + 3] + w3 * xv[p + 4];
	v_lshlrev_b32_e32 v27, 16, v39
	v_cndmask_b32_e64 v19, 0, 1.0, vcc
	v_mul_f32_e32 v25, v19, v21
	v_or_b32_e32 v19, 19, v37
	v_cmp_lt_u32_e32 vcc, v19, v5
	v_lshlrev_b32_e32 v21, 16, v29
	v_fmac_f32_e32 v14, v3, v10
	v_cndmask_b32_e64 v19, 0, 1.0, vcc
	v_mul_f32_e32 v23, v19, v21
	v_or_b32_e32 v19, 20, v37
	v_cmp_lt_u32_e32 vcc, v19, v5
	v_lshlrev_b32_e32 v21, 16, v31
	ds_read_u16 v29, v186 offset:3072
	ds_read_u16 v31, v186 offset:3200
	ds_read_u16 v39, v186 offset:3328
	ds_read_u16 v40, v186 offset:3456
	ds_read_u16 v41, v186 offset:3584
	ds_read_u16 v43, v186 offset:3712
	ds_read_u16 v45, v186 offset:3840
	ds_read_u16 v47, v186 offset:3968
	v_cndmask_b32_e64 v19, 0, 1.0, vcc
	v_mul_f32_e32 v21, v19, v21
	v_or_b32_e32 v19, 21, v37
	v_cmp_lt_u32_e32 vcc, v19, v5
	s_waitcnt lgkmcnt(7)
	v_lshlrev_b32_e32 v29, 16, v29
	v_fmac_f32_e32 v12, v1, v10
	v_cndmask_b32_e64 v19, 0, 1.0, vcc
	v_mul_f32_e32 v19, v19, v27
	v_or_b32_e32 v27, 22, v37
	v_cmp_lt_u32_e32 vcc, v27, v5
	v_fma_f32 v10, v0, v10, v4
	v_fmac_f32_e32 v14, v2, v9
	v_cndmask_b32_e64 v27, 0, 1.0, vcc
	v_mul_f32_e32 v46, v27, v29
	v_or_b32_e32 v27, 23, v37
	v_cmp_lt_u32_e32 vcc, v27, v5
	s_waitcnt lgkmcnt(6)
	v_lshlrev_b32_e32 v29, 16, v31
	v_fmac_f32_e32 v12, v3, v9
	v_cndmask_b32_e64 v27, 0, 1.0, vcc
	v_mul_f32_e32 v44, v27, v29
	v_or_b32_e32 v27, 24, v37
	v_cmp_lt_u32_e32 vcc, v27, v5
	s_waitcnt lgkmcnt(5)
	v_lshlrev_b32_e32 v29, 16, v39
	v_fmac_f32_e32 v10, v1, v9
	v_cndmask_b32_e64 v27, 0, 1.0, vcc
	v_mul_f32_e32 v42, v27, v29
	v_or_b32_e32 v27, 25, v37
	v_cmp_lt_u32_e32 vcc, v27, v5
	s_waitcnt lgkmcnt(4)
	v_lshlrev_b32_e32 v29, 16, v40
	v_fma_f32 v9, v0, v9, v4
	v_cndmask_b32_e64 v27, 0, 1.0, vcc
	v_mul_f32_e32 v40, v27, v29
	v_or_b32_e32 v27, 26, v37
	v_cmp_lt_u32_e32 vcc, v27, v5
	s_waitcnt lgkmcnt(3)
	v_lshlrev_b32_e32 v29, 16, v41
	s_waitcnt lgkmcnt(0)
	v_lshlrev_b32_e32 v41, 16, v47
	v_cndmask_b32_e64 v27, 0, 1.0, vcc
	v_mul_f32_e32 v39, v27, v29
	v_or_b32_e32 v27, 27, v37
	v_cmp_lt_u32_e32 vcc, v27, v5
	v_lshlrev_b32_e32 v29, 16, v43
	v_fmac_f32_e32 v12, v2, v8
	v_cndmask_b32_e64 v27, 0, 1.0, vcc
	v_mul_f32_e32 v31, v27, v29
	v_or_b32_e32 v27, 28, v37
	v_cmp_lt_u32_e32 vcc, v27, v5
	v_lshlrev_b32_e32 v29, 16, v45
	ds_read_u16 v43, v186 offset:4096
	ds_read_u16 v45, v186 offset:4224
	ds_read_u16 v47, v186 offset:4352
	ds_read_u16 v48, v186 offset:4480
	ds_read_u16 v49, v186 offset:4608
	ds_read_u16 v51, v186 offset:4736
	ds_read_u16 v53, v186 offset:4864
	ds_read_u16 v55, v186 offset:4992
	v_cndmask_b32_e64 v27, 0, 1.0, vcc
	v_mul_f32_e32 v29, v27, v29
	v_or_b32_e32 v27, 29, v37
	v_cmp_lt_u32_e32 vcc, v27, v5
	s_waitcnt lgkmcnt(7)
	v_lshlrev_b32_e32 v43, 16, v43
	v_fmac_f32_e32 v10, v3, v8
	v_cndmask_b32_e64 v27, 0, 1.0, vcc
	v_mul_f32_e32 v27, v27, v41
	v_or_b32_e32 v41, 30, v37
	v_cmp_lt_u32_e32 vcc, v41, v5
	v_fmac_f32_e32 v9, v1, v8
	v_fma_f32 v8, v0, v8, v4
	v_cndmask_b32_e64 v41, 0, 1.0, vcc
	v_mul_f32_e32 v54, v41, v43
	v_or_b32_e32 v41, 31, v37
	v_cmp_lt_u32_e32 vcc, v41, v5
	s_waitcnt lgkmcnt(6)
	v_lshlrev_b32_e32 v43, 16, v45
	v_fmac_f32_e32 v10, v2, v7
	v_cndmask_b32_e64 v41, 0, 1.0, vcc
	v_mul_f32_e32 v52, v41, v43
	v_or_b32_e32 v41, 32, v37
	v_cmp_lt_u32_e32 vcc, v41, v5
	s_waitcnt lgkmcnt(5)
	v_lshlrev_b32_e32 v43, 16, v47
	v_fmac_f32_e32 v9, v3, v7
	v_cndmask_b32_e64 v41, 0, 1.0, vcc
	v_mul_f32_e32 v50, v41, v43
	v_or_b32_e32 v41, 33, v37
	v_cmp_lt_u32_e32 vcc, v41, v5
	s_waitcnt lgkmcnt(4)
	v_lshlrev_b32_e32 v43, 16, v48
	v_fmac_f32_e32 v8, v1, v7
	v_cndmask_b32_e64 v41, 0, 1.0, vcc
	v_mul_f32_e32 v48, v41, v43
	v_or_b32_e32 v41, 34, v37
	v_cmp_lt_u32_e32 vcc, v41, v5
	s_waitcnt lgkmcnt(3)
	v_lshlrev_b32_e32 v43, 16, v49
	s_waitcnt lgkmcnt(0)
	v_lshlrev_b32_e32 v49, 16, v55
	v_cndmask_b32_e64 v41, 0, 1.0, vcc
	v_mul_f32_e32 v47, v41, v43
	v_or_b32_e32 v41, 35, v37
	v_cmp_lt_u32_e32 vcc, v41, v5
	v_lshlrev_b32_e32 v43, 16, v51
	v_fma_f32 v7, v0, v7, v4
	v_cndmask_b32_e64 v41, 0, 1.0, vcc
	v_mul_f32_e32 v45, v41, v43
	v_or_b32_e32 v41, 36, v37
	v_cmp_lt_u32_e32 vcc, v41, v5
	v_lshlrev_b32_e32 v43, 16, v53
	ds_read_u16 v51, v186 offset:5120
	ds_read_u16 v53, v186 offset:5248
	ds_read_u16 v55, v186 offset:5376
	ds_read_u16 v56, v186 offset:5504
	ds_read_u16 v57, v186 offset:5632
	ds_read_u16 v59, v186 offset:5760
	ds_read_u16 v61, v186 offset:5888
	ds_read_u16 v63, v186 offset:6016
	v_cndmask_b32_e64 v41, 0, 1.0, vcc
	v_mul_f32_e32 v43, v41, v43
	v_or_b32_e32 v41, 37, v37
	v_cmp_lt_u32_e32 vcc, v41, v5
	s_waitcnt lgkmcnt(7)
	v_lshlrev_b32_e32 v51, 16, v51
	v_fmac_f32_e32 v9, v2, v6
	v_cndmask_b32_e64 v41, 0, 1.0, vcc
	v_mul_f32_e32 v41, v41, v49
	v_or_b32_e32 v49, 38, v37
	v_cmp_lt_u32_e32 vcc, v49, v5
	v_fmac_f32_e32 v8, v3, v6
	v_fmac_f32_e32 v7, v1, v6
	v_cndmask_b32_e64 v49, 0, 1.0, vcc
	v_mul_f32_e32 v62, v49, v51
	v_or_b32_e32 v49, 39, v37
	v_cmp_lt_u32_e32 vcc, v49, v5
	s_waitcnt lgkmcnt(6)
	v_lshlrev_b32_e32 v51, 16, v53
	v_fma_f32 v6, v0, v6, v4
	v_cndmask_b32_e64 v49, 0, 1.0, vcc
	v_mul_f32_e32 v60, v49, v51
	v_or_b32_e32 v49, 40, v37
	v_cmp_lt_u32_e32 vcc, v49, v5
	s_waitcnt lgkmcnt(5)
	v_lshlrev_b32_e32 v51, 16, v55
	v_fmac_f32_e32 v6, v1, v24
	v_cndmask_b32_e64 v49, 0, 1.0, vcc
	v_mul_f32_e32 v58, v49, v51
	v_or_b32_e32 v49, 41, v37
	v_cmp_lt_u32_e32 vcc, v49, v5
	s_waitcnt lgkmcnt(4)
	v_lshlrev_b32_e32 v51, 16, v56
	v_fmac_f32_e32 v8, v2, v24
	v_cndmask_b32_e64 v49, 0, 1.0, vcc
	v_mul_f32_e32 v56, v49, v51
	v_or_b32_e32 v49, 42, v37
	v_cmp_lt_u32_e32 vcc, v49, v5
	s_waitcnt lgkmcnt(3)
	v_lshlrev_b32_e32 v51, 16, v57
	s_waitcnt lgkmcnt(0)
; __device__ __forceinline__ float bf2f(unsigned short b) { return __uint_as_float(((unsigned)b) << 16); }
; __device__ __forceinline__ unsigned cvt_pk_bf16(float lo, float hi) { unsigned r; asm volatile("v_cvt_pk_bf16_f32 %0, %1, %2" : "=v"(r) : "v"(lo), "v"(hi)); return r; }
; __device__ __forceinline__ int lru_pass1(const Params& P, int l, LAS unsigned char* lds, unsigned* qw) {
;     ...
;             for (int i = 0; i < 67; ++i) { const int n = n0 - 2 + i; xv[i] = bf2f(xaS[i * 64 + lane]) * ((n >= 0 && n < Ls) ? 1.0f : 0.0f); }
; #pragma unroll
;             for (int p = 0; p < 64; p += 2) { const float xc0 = cb + w0 * xv[p] + w1 * xv[p + 1] + w2 * xv[p + 2] + w3 * xv[p + 3], xc1 = cb + w0 * xv[p + 1] + w1 * xv[p + 2] + w2 * xv[p + 3] + w3 * xv[p + 4];
;                 const unsigned pk = cvt_pk_bf16(xc0, xc1); xcS[p * 72 + lane] = (unsigned short)pk; xcS[(p + 1) * 72 + lane] = (unsigned short)(pk >> 16); }
	v_lshlrev_b32_e32 v57, 16, v63
	v_cndmask_b32_e64 v49, 0, 1.0, vcc
	v_mul_f32_e32 v55, v49, v51
	v_or_b32_e32 v49, 43, v37
	v_cmp_lt_u32_e32 vcc, v49, v5
	v_lshlrev_b32_e32 v51, 16, v59
	v_fmac_f32_e32 v6, v3, v22
	v_cndmask_b32_e64 v49, 0, 1.0, vcc
	v_mul_f32_e32 v53, v49, v51
	v_or_b32_e32 v49, 44, v37
	v_cmp_lt_u32_e32 vcc, v49, v5
	v_lshlrev_b32_e32 v51, 16, v61
	ds_read_u16 v59, v186 offset:6144
	ds_read_u16 v61, v186 offset:6272
	ds_read_u16 v63, v186 offset:6400
	ds_read_u16 v64, v186 offset:6528
	ds_read_u16 v66, v186 offset:6656
	ds_read_u16 v67, v186 offset:6784
	ds_read_u16 v69, v186 offset:6912
	ds_read_u16 v71, v186 offset:7040
	v_cndmask_b32_e64 v49, 0, 1.0, vcc
	v_mul_f32_e32 v51, v49, v51
	v_or_b32_e32 v49, 45, v37
	v_cmp_lt_u32_e32 vcc, v49, v5
	s_waitcnt lgkmcnt(7)
	v_lshlrev_b32_e32 v59, 16, v59
	v_fmac_f32_e32 v7, v3, v24
	v_cndmask_b32_e64 v49, 0, 1.0, vcc
	v_mul_f32_e32 v49, v49, v57
	v_or_b32_e32 v57, 46, v37
	v_cmp_lt_u32_e32 vcc, v57, v5
	v_fmac_f32_e32 v6, v2, v20
	v_fmac_f32_e32 v7, v2, v22
	v_cndmask_b32_e64 v57, 0, 1.0, vcc
	v_mul_f32_e32 v70, v57, v59
	v_or_b32_e32 v57, 47, v37
	v_cmp_lt_u32_e32 vcc, v57, v5
	s_waitcnt lgkmcnt(6)
	v_lshlrev_b32_e32 v59, 16, v61
	v_lshl_or_b32 v128, v32, 7, v206
	v_cndmask_b32_e64 v57, 0, 1.0, vcc
	v_mul_f32_e32 v68, v57, v59
	v_or_b32_e32 v57, 48, v37
	v_cmp_lt_u32_e32 vcc, v57, v5
	s_waitcnt lgkmcnt(5)
	v_lshlrev_b32_e32 v59, 16, v63
	s_mov_b64 s[50:51], 0
	v_cndmask_b32_e64 v57, 0, 1.0, vcc
	v_mul_f32_e32 v65, v57, v59
	v_or_b32_e32 v57, 49, v37
	v_cmp_lt_u32_e32 vcc, v57, v5
	s_waitcnt lgkmcnt(4)
	v_lshlrev_b32_e32 v59, 16, v64
	v_mov_b64_e32 v[156:157], v[128:129]
	v_cndmask_b32_e64 v57, 0, 1.0, vcc
	v_mul_f32_e32 v64, v57, v59
	v_or_b32_e32 v57, 50, v37
	v_cmp_lt_u32_e32 vcc, v57, v5
	s_waitcnt lgkmcnt(3)
	v_lshlrev_b32_e32 v59, 16, v66
	s_waitcnt lgkmcnt(0)
	v_lshlrev_b32_e32 v66, 16, v71
	v_cndmask_b32_e64 v57, 0, 1.0, vcc
	v_mul_f32_e32 v63, v57, v59
	v_or_b32_e32 v57, 51, v37
	v_cmp_lt_u32_e32 vcc, v57, v5
	v_lshlrev_b32_e32 v59, 16, v67
	v_mov_b32_e32 v213, v207
	v_cndmask_b32_e64 v57, 0, 1.0, vcc
	v_mul_f32_e32 v61, v57, v59
	v_or_b32_e32 v57, 52, v37
	v_cmp_lt_u32_e32 vcc, v57, v5
	v_lshlrev_b32_e32 v59, 16, v69
	ds_read_u16 v67, v186 offset:7168
	ds_read_u16 v69, v186 offset:7296
	ds_read_u16 v71, v186 offset:7424
	ds_read_u16 v72, v186 offset:7552
	ds_read_u16 v74, v186 offset:7680
	ds_read_u16 v75, v186 offset:7808
	ds_read_u16 v78, v186 offset:7936
	ds_read_u16 v79, v186 offset:8064
	v_cndmask_b32_e64 v57, 0, 1.0, vcc
	v_mul_f32_e32 v59, v57, v59
	v_or_b32_e32 v57, 53, v37
	v_cmp_lt_u32_e32 vcc, v57, v5
	s_waitcnt lgkmcnt(7)
	v_lshlrev_b32_e32 v67, 16, v67
	v_cndmask_b32_e64 v57, 0, 1.0, vcc
	v_mul_f32_e32 v57, v57, v66
	v_or_b32_e32 v66, 54, v37
	v_cmp_lt_u32_e32 vcc, v66, v5
	s_nop 1
	v_cndmask_b32_e64 v66, 0, 1.0, vcc
	v_mul_f32_e32 v77, v66, v67
	v_or_b32_e32 v66, 55, v37
	v_cmp_lt_u32_e32 vcc, v66, v5
	s_waitcnt lgkmcnt(6)
	v_lshlrev_b32_e32 v67, 16, v69
	v_cndmask_b32_e64 v66, 0, 1.0, vcc
	v_mul_f32_e32 v76, v66, v67
	v_or_b32_e32 v66, 56, v37
	v_cmp_lt_u32_e32 vcc, v66, v5
	s_waitcnt lgkmcnt(5)
	v_lshlrev_b32_e32 v67, 16, v71
	v_cndmask_b32_e64 v66, 0, 1.0, vcc
	v_mul_f32_e32 v73, v66, v67
	v_or_b32_e32 v66, 57, v37
	v_cmp_lt_u32_e32 vcc, v66, v5
	s_waitcnt lgkmcnt(4)
	v_lshlrev_b32_e32 v67, 16, v72
	v_cndmask_b32_e64 v66, 0, 1.0, vcc
	v_mul_f32_e32 v72, v66, v67
	v_or_b32_e32 v66, 58, v37
	v_cmp_lt_u32_e32 vcc, v66, v5
	s_waitcnt lgkmcnt(3)
	v_lshlrev_b32_e32 v67, 16, v74
	s_waitcnt lgkmcnt(0)
	v_lshlrev_b32_e32 v74, 16, v79
	v_cndmask_b32_e64 v66, 0, 1.0, vcc
	v_mul_f32_e32 v71, v66, v67
	v_or_b32_e32 v66, 59, v37
	v_cmp_lt_u32_e32 vcc, v66, v5
	v_lshlrev_b32_e32 v67, 16, v75
	ds_read_u16 v75, v186 offset:8192
	v_cndmask_b32_e64 v66, 0, 1.0, vcc
	v_mul_f32_e32 v69, v66, v67
	v_lshlrev_b32_e32 v67, 16, v78
	ds_read_u16 v78, v186 offset:8320
	ds_read_u16 v79, v186 offset:8448
	v_cvt_pk_bf16_f32 v14, v16, v14
	ds_write_b16 v187, v14
	ds_write_b16_d16_hi v187, v14 offset:144
	v_cvt_pk_bf16_f32 v10, v12, v10
	ds_write_b16 v187, v10 offset:288
	ds_write_b16_d16_hi v187, v10 offset:432
	v_cvt_pk_bf16_f32 v8, v9, v8
	ds_write_b16 v187, v8 offset:576
	ds_write_b16_d16_hi v187, v8 offset:720
	v_cvt_pk_bf16_f32 v6, v7, v6
	ds_write_b16 v187, v6 offset:864
	ds_write_b16_d16_hi v187, v6 offset:1008
	v_fma_f32 v6, v0, v24, v4
	v_fmac_f32_e32 v6, v1, v22
	v_fma_f32 v7, v0, v22, v4
	v_fmac_f32_e32 v6, v3, v20
	v_fmac_f32_e32 v7, v1, v20
	v_fmac_f32_e32 v6, v2, v18
	v_fmac_f32_e32 v7, v3, v18
	v_fmac_f32_e32 v7, v2, v17
	v_cvt_pk_bf16_f32 v6, v6, v7
	ds_write_b16 v187, v6 offset:1152
	ds_write_b16_d16_hi v187, v6 offset:1296
	v_fma_f32 v6, v0, v20, v4
	v_fmac_f32_e32 v6, v1, v18
	v_fma_f32 v7, v0, v18, v4
	v_fmac_f32_e32 v6, v3, v17
	v_fmac_f32_e32 v7, v1, v17
	v_fmac_f32_e32 v6, v2, v15
	v_fmac_f32_e32 v7, v3, v15
	v_fmac_f32_e32 v7, v2, v13
	v_cvt_pk_bf16_f32 v6, v6, v7
	ds_write_b16 v187, v6 offset:1440
	ds_write_b16_d16_hi v187, v6 offset:1584
	v_fma_f32 v6, v0, v17, v4
	v_fmac_f32_e32 v6, v1, v15
	v_fma_f32 v7, v0, v15, v4
	v_fmac_f32_e32 v6, v3, v13
	v_fmac_f32_e32 v7, v1, v13
	v_fmac_f32_e32 v6, v2, v11
	v_fmac_f32_e32 v7, v3, v11
	v_fmac_f32_e32 v7, v2, v38
	v_cvt_pk_bf16_f32 v6, v6, v7
	ds_write_b16 v187, v6 offset:1728
	ds_write_b16_d16_hi v187, v6 offset:1872
	v_fma_f32 v6, v0, v13, v4
	v_fmac_f32_e32 v6, v1, v11
	v_fma_f32 v7, v0, v11, v4
	v_fmac_f32_e32 v6, v3, v38
	v_fmac_f32_e32 v7, v1, v38
	v_fmac_f32_e32 v6, v2, v30
	v_fmac_f32_e32 v7, v3, v30
	v_fmac_f32_e32 v7, v2, v28
	v_cvt_pk_bf16_f32 v6, v6, v7
	ds_write_b16 v187, v6 offset:2016
; __device__ __forceinline__ unsigned cvt_pk_bf16(float lo, float hi) { unsigned r; asm volatile("v_cvt_pk_bf16_f32 %0, %1, %2" : "=v"(r) : "v"(lo), "v"(hi)); return r; }
; __device__ __forceinline__ int lru_pass1(const Params& P, int l, LAS unsigned char* lds, unsigned* qw) {
;     ...
;             for (int p = 0; p < 64; p += 2) { const float xc0 = cb + w0 * xv[p] + w1 * xv[p + 1] + w2 * xv[p + 2] + w3 * xv[p + 3], xc1 = cb + w0 * xv[p + 1] + w1 * xv[p + 2] + w2 * xv[p + 3] + w3 * xv[p + 4];
;                 const unsigned pk = cvt_pk_bf16(xc0, xc1); xcS[p * 72 + lane] = (unsigned short)pk; xcS[(p + 1) * 72 + lane] = (unsigned short)(pk >> 16); }
	ds_write_b16_d16_hi v187, v6 offset:2160
	v_fma_f32 v6, v0, v38, v4
	v_fmac_f32_e32 v6, v1, v30
	v_fma_f32 v7, v0, v30, v4
	v_fmac_f32_e32 v6, v3, v28
	v_fmac_f32_e32 v7, v1, v28
	v_fmac_f32_e32 v6, v2, v26
	v_fmac_f32_e32 v7, v3, v26
	v_fmac_f32_e32 v7, v2, v25
	v_cvt_pk_bf16_f32 v6, v6, v7
	ds_write_b16 v187, v6 offset:2304
	ds_write_b16_d16_hi v187, v6 offset:2448
	v_fma_f32 v6, v0, v28, v4
	v_fmac_f32_e32 v6, v1, v26
	v_fma_f32 v7, v0, v26, v4
	v_fmac_f32_e32 v6, v3, v25
	v_fmac_f32_e32 v7, v1, v25
	v_fmac_f32_e32 v6, v2, v23
	v_fmac_f32_e32 v7, v3, v23
	v_fmac_f32_e32 v7, v2, v21
	v_cvt_pk_bf16_f32 v6, v6, v7
	ds_write_b16 v187, v6 offset:2592
	ds_write_b16_d16_hi v187, v6 offset:2736
	v_fma_f32 v6, v0, v25, v4
	v_fmac_f32_e32 v6, v1, v23
	v_fma_f32 v7, v0, v23, v4
	v_fmac_f32_e32 v6, v3, v21
	v_fmac_f32_e32 v7, v1, v21
	v_fmac_f32_e32 v6, v2, v19
	v_fmac_f32_e32 v7, v3, v19
	v_fmac_f32_e32 v7, v2, v46
	v_cvt_pk_bf16_f32 v6, v6, v7
	ds_write_b16 v187, v6 offset:2880
	ds_write_b16_d16_hi v187, v6 offset:3024
	v_fma_f32 v6, v0, v21, v4
	v_fmac_f32_e32 v6, v1, v19
	v_fma_f32 v7, v0, v19, v4
	v_fmac_f32_e32 v6, v3, v46
	v_fmac_f32_e32 v7, v1, v46
	v_fmac_f32_e32 v6, v2, v44
	v_fmac_f32_e32 v7, v3, v44
	v_fmac_f32_e32 v7, v2, v42
	v_cvt_pk_bf16_f32 v6, v6, v7
	ds_write_b16 v187, v6 offset:3168
	ds_write_b16_d16_hi v187, v6 offset:3312
	v_fma_f32 v6, v0, v46, v4
	v_fmac_f32_e32 v6, v1, v44
	v_fma_f32 v7, v0, v44, v4
	v_fmac_f32_e32 v6, v3, v42
	v_fmac_f32_e32 v7, v1, v42
	v_fmac_f32_e32 v6, v2, v40
	v_fmac_f32_e32 v7, v3, v40
	v_fmac_f32_e32 v7, v2, v39
	v_cvt_pk_bf16_f32 v6, v6, v7
	ds_write_b16 v187, v6 offset:3456
	ds_write_b16_d16_hi v187, v6 offset:3600
	v_fma_f32 v6, v0, v42, v4
	v_fmac_f32_e32 v6, v1, v40
	v_fma_f32 v7, v0, v40, v4
	v_fmac_f32_e32 v6, v3, v39
	v_fmac_f32_e32 v7, v1, v39
	v_fmac_f32_e32 v6, v2, v31
	v_fmac_f32_e32 v7, v3, v31
	v_fmac_f32_e32 v7, v2, v29
	v_cvt_pk_bf16_f32 v6, v6, v7
	ds_write_b16 v187, v6 offset:3744
	ds_write_b16_d16_hi v187, v6 offset:3888
	v_fma_f32 v6, v0, v39, v4
	v_fmac_f32_e32 v6, v1, v31
	v_fma_f32 v7, v0, v31, v4
	v_fmac_f32_e32 v6, v3, v29
	v_fmac_f32_e32 v7, v1, v29
	v_fmac_f32_e32 v6, v2, v27
	v_fmac_f32_e32 v7, v3, v27
	v_fmac_f32_e32 v7, v2, v54
	v_cvt_pk_bf16_f32 v6, v6, v7
	ds_write_b16 v187, v6 offset:4032
	ds_write_b16_d16_hi v187, v6 offset:4176
	v_fma_f32 v6, v0, v29, v4
	v_fmac_f32_e32 v6, v1, v27
	v_fma_f32 v7, v0, v27, v4
	v_fmac_f32_e32 v6, v3, v54
	v_fmac_f32_e32 v7, v1, v54
	v_fmac_f32_e32 v6, v2, v52
	v_fmac_f32_e32 v7, v3, v52
	v_fmac_f32_e32 v7, v2, v50
	v_cvt_pk_bf16_f32 v6, v6, v7
	ds_write_b16 v187, v6 offset:4320
	ds_write_b16_d16_hi v187, v6 offset:4464
	v_fma_f32 v6, v0, v54, v4
	v_fmac_f32_e32 v6, v1, v52
	v_fma_f32 v7, v0, v52, v4
	v_fmac_f32_e32 v6, v3, v50
	v_fmac_f32_e32 v7, v1, v50
	v_fmac_f32_e32 v6, v2, v48
	v_fmac_f32_e32 v7, v3, v48
	v_fmac_f32_e32 v7, v2, v47
	v_cvt_pk_bf16_f32 v6, v6, v7
	ds_write_b16 v187, v6 offset:4608
	ds_write_b16_d16_hi v187, v6 offset:4752
	v_fma_f32 v6, v0, v50, v4
	v_fmac_f32_e32 v6, v1, v48
	v_fma_f32 v7, v0, v48, v4
	v_fmac_f32_e32 v6, v3, v47
	v_fmac_f32_e32 v7, v1, v47
	v_fmac_f32_e32 v6, v2, v45
	v_fmac_f32_e32 v7, v3, v45
	v_fmac_f32_e32 v7, v2, v43
	v_cvt_pk_bf16_f32 v6, v6, v7
	ds_write_b16 v187, v6 offset:4896
	ds_write_b16_d16_hi v187, v6 offset:5040
	v_fma_f32 v6, v0, v47, v4
	v_fmac_f32_e32 v6, v1, v45
	v_fma_f32 v7, v0, v45, v4
	v_fmac_f32_e32 v6, v3, v43
	v_fmac_f32_e32 v7, v1, v43
	v_fmac_f32_e32 v6, v2, v41
	v_fmac_f32_e32 v7, v3, v41
	v_fmac_f32_e32 v7, v2, v62
	v_cvt_pk_bf16_f32 v6, v6, v7
	ds_write_b16 v187, v6 offset:5184
	ds_write_b16_d16_hi v187, v6 offset:5328
	v_fma_f32 v6, v0, v43, v4
	v_fmac_f32_e32 v6, v1, v41
	v_fma_f32 v7, v0, v41, v4
	v_fmac_f32_e32 v6, v3, v62
	v_fmac_f32_e32 v7, v1, v62
	v_fmac_f32_e32 v6, v2, v60
	v_fmac_f32_e32 v7, v3, v60
	v_fmac_f32_e32 v7, v2, v58
	v_cvt_pk_bf16_f32 v6, v6, v7
	ds_write_b16 v187, v6 offset:5472
	ds_write_b16_d16_hi v187, v6 offset:5616
	v_fma_f32 v6, v0, v62, v4
	v_fmac_f32_e32 v6, v1, v60
	v_fma_f32 v7, v0, v60, v4
	v_fmac_f32_e32 v6, v3, v58
	v_fmac_f32_e32 v7, v1, v58
	v_fmac_f32_e32 v6, v2, v56
	v_fmac_f32_e32 v7, v3, v56
	v_fmac_f32_e32 v7, v2, v55
	v_cvt_pk_bf16_f32 v6, v6, v7
	ds_write_b16 v187, v6 offset:5760
	ds_write_b16_d16_hi v187, v6 offset:5904
	v_fma_f32 v6, v0, v58, v4
	v_fmac_f32_e32 v6, v1, v56
	v_fma_f32 v7, v0, v56, v4
	v_fmac_f32_e32 v6, v3, v55
	v_fmac_f32_e32 v7, v1, v55
	v_fmac_f32_e32 v6, v2, v53
	v_fmac_f32_e32 v7, v3, v53
	v_fmac_f32_e32 v7, v2, v51
	v_cvt_pk_bf16_f32 v6, v6, v7
	ds_write_b16 v187, v6 offset:6048
	ds_write_b16_d16_hi v187, v6 offset:6192
	v_fma_f32 v6, v0, v55, v4
	v_fmac_f32_e32 v6, v1, v53
	v_fma_f32 v7, v0, v53, v4
	v_fmac_f32_e32 v6, v3, v51
	v_fmac_f32_e32 v7, v1, v51
	v_fmac_f32_e32 v6, v2, v49
	v_fmac_f32_e32 v7, v3, v49
	v_fmac_f32_e32 v7, v2, v70
	v_cvt_pk_bf16_f32 v6, v6, v7
	ds_write_b16 v187, v6 offset:6336
	ds_write_b16_d16_hi v187, v6 offset:6480
	v_fma_f32 v6, v0, v51, v4
	v_fmac_f32_e32 v6, v1, v49
	v_fma_f32 v7, v0, v49, v4
	v_fmac_f32_e32 v6, v3, v70
	v_fmac_f32_e32 v7, v1, v70
	v_fmac_f32_e32 v6, v2, v68
	v_fmac_f32_e32 v7, v3, v68
	v_fmac_f32_e32 v7, v2, v65
	v_cvt_pk_bf16_f32 v6, v6, v7
	ds_write_b16 v187, v6 offset:6624
	ds_write_b16_d16_hi v187, v6 offset:6768
	v_fma_f32 v6, v0, v70, v4
	v_fmac_f32_e32 v6, v1, v68
; #define LAS __attribute__((address_space(3)))
; __device__ __forceinline__ unsigned cvt_pk_bf16(float lo, float hi) { unsigned r; asm volatile("v_cvt_pk_bf16_f32 %0, %1, %2" : "=v"(r) : "v"(lo), "v"(hi)); return r; }
; __device__ __forceinline__ int lru_pass1(const Params& P, int l, LAS unsigned char* lds, unsigned* qw) {
;     ...
;             for (int p = 0; p < 64; p += 2) { const float xc0 = cb + w0 * xv[p] + w1 * xv[p + 1] + w2 * xv[p + 2] + w3 * xv[p + 3], xc1 = cb + w0 * xv[p + 1] + w1 * xv[p + 2] + w2 * xv[p + 3] + w3 * xv[p + 4];
;                 const unsigned pk = cvt_pk_bf16(xc0, xc1); xcS[p * 72 + lane] = (unsigned short)pk; xcS[(p + 1) * 72 + lane] = (unsigned short)(pk >> 16); }
;         }
;         asm volatile("s_waitcnt lgkmcnt(0)" ::: "memory");
;         bf16x8 Af[4][2];
; #pragma unroll
;         for (int mt = 0; mt < 4; ++mt)
; #pragma unroll
;             for (int kk = 0; kk < 2; ++kk) { const int row = 16 * (fr >> 2) + 4 * mt + (fr & 3); Af[mt][kk] = *(const LAS bf16x8*)(xcS + row * 72 + kk * 32 + 8 * fq); }
	v_fma_f32 v7, v0, v68, v4
	v_fmac_f32_e32 v6, v3, v65
	v_fmac_f32_e32 v7, v1, v65
	v_fmac_f32_e32 v6, v2, v64
	v_fmac_f32_e32 v7, v3, v64
	v_fmac_f32_e32 v7, v2, v63
	v_cvt_pk_bf16_f32 v6, v6, v7
	ds_write_b16 v187, v6 offset:6912
	ds_write_b16_d16_hi v187, v6 offset:7056
	v_fma_f32 v6, v0, v65, v4
	v_fmac_f32_e32 v6, v1, v64
	v_fma_f32 v7, v0, v64, v4
	v_fmac_f32_e32 v6, v3, v63
	v_fmac_f32_e32 v7, v1, v63
	v_fmac_f32_e32 v6, v2, v61
	v_fmac_f32_e32 v7, v3, v61
	v_fmac_f32_e32 v7, v2, v59
	v_cvt_pk_bf16_f32 v6, v6, v7
	ds_write_b16 v187, v6 offset:7200
	ds_write_b16_d16_hi v187, v6 offset:7344
	v_fma_f32 v6, v0, v63, v4
	v_fmac_f32_e32 v6, v1, v61
	v_fma_f32 v7, v0, v61, v4
	v_fmac_f32_e32 v6, v3, v59
	v_fmac_f32_e32 v7, v1, v59
	v_fmac_f32_e32 v6, v2, v57
	v_fmac_f32_e32 v7, v3, v57
	v_fmac_f32_e32 v7, v2, v77
	v_cvt_pk_bf16_f32 v6, v6, v7
	ds_write_b16 v187, v6 offset:7488
	ds_write_b16_d16_hi v187, v6 offset:7632
	v_fma_f32 v6, v0, v59, v4
	v_fmac_f32_e32 v6, v1, v57
	v_fma_f32 v7, v0, v57, v4
	v_fmac_f32_e32 v6, v3, v77
	v_fmac_f32_e32 v7, v1, v77
	v_fmac_f32_e32 v6, v2, v76
	v_fmac_f32_e32 v7, v3, v76
	v_or_b32_e32 v66, 60, v37
	v_fmac_f32_e32 v7, v2, v73
	v_cvt_pk_bf16_f32 v6, v6, v7
	v_cmp_lt_u32_e32 vcc, v66, v5
	ds_write_b16 v187, v6 offset:7776
	ds_write_b16_d16_hi v187, v6 offset:7920
	v_fma_f32 v6, v0, v77, v4
	v_cndmask_b32_e64 v66, 0, 1.0, vcc
	v_fmac_f32_e32 v6, v1, v76
	v_fma_f32 v7, v0, v76, v4
	v_mul_f32_e32 v66, v66, v67
	v_or_b32_e32 v67, 61, v37
	v_fmac_f32_e32 v6, v3, v73
	v_fmac_f32_e32 v7, v1, v73
	v_cmp_lt_u32_e32 vcc, v67, v5
	v_fmac_f32_e32 v6, v2, v72
	v_fmac_f32_e32 v7, v3, v72
	v_cndmask_b32_e64 v67, 0, 1.0, vcc
	v_fmac_f32_e32 v7, v2, v71
	v_cvt_pk_bf16_f32 v6, v6, v7
	v_mul_f32_e32 v67, v67, v74
	v_or_b32_e32 v74, 62, v37
	ds_write_b16 v187, v6 offset:8064
	ds_write_b16_d16_hi v187, v6 offset:8208
	v_fma_f32 v6, v0, v73, v4
	v_cmp_lt_u32_e32 vcc, v74, v5
	v_fmac_f32_e32 v6, v1, v72
	v_fma_f32 v7, v0, v72, v4
	s_waitcnt lgkmcnt(14)
	v_lshlrev_b32_e32 v75, 16, v75
	v_cndmask_b32_e64 v74, 0, 1.0, vcc
	v_fmac_f32_e32 v6, v3, v71
	v_fmac_f32_e32 v7, v1, v71
	v_mul_f32_e32 v74, v74, v75
	v_or_b32_e32 v75, 63, v37
	v_fmac_f32_e32 v6, v2, v69
	v_fmac_f32_e32 v7, v3, v69
	v_cmp_lt_u32_e32 vcc, v75, v5
	v_fmac_f32_e32 v7, v2, v66
	v_cvt_pk_bf16_f32 v6, v6, v7
	v_lshlrev_b32_e32 v78, 16, v78
	v_cndmask_b32_e64 v75, 0, 1.0, vcc
	ds_write_b16 v187, v6 offset:8352
	ds_write_b16_d16_hi v187, v6 offset:8496
	v_fma_f32 v6, v0, v71, v4
	v_mul_f32_e32 v75, v75, v78
	v_add_u32_e32 v78, 64, v37
	v_fmac_f32_e32 v6, v1, v69
	v_fma_f32 v7, v0, v69, v4
	v_ashrrev_i32_e32 v37, 31, v36
	v_fmac_f32_e32 v6, v3, v66
	v_fmac_f32_e32 v7, v1, v66
	v_lshlrev_b64 v[104:105], 10, v[36:37]
	v_fmac_f32_e32 v6, v2, v67
	v_fmac_f32_e32 v7, v3, v67
	v_lshl_add_u64 v[106:107], v[104:105], 0, s[0:1]
	s_mov_b64 s[0:1], 0xc00
	v_fmac_f32_e32 v7, v2, v74
	v_cvt_pk_bf16_f32 v6, v6, v7
	v_lshl_add_u64 v[110:111], v[104:105], 0, s[0:1]
	s_mov_b64 s[0:1], 0x1000
	v_cmp_lt_u32_e32 vcc, v78, v5
	ds_write_b16 v187, v6 offset:8640
	ds_write_b16_d16_hi v187, v6 offset:8784
	v_fma_f32 v6, v0, v66, v4
	v_fmac_f32_e32 v4, v0, v67
	v_lshl_add_u64 v[112:113], v[104:105], 0, s[0:1]
	s_mov_b64 s[0:1], 0x1400
	v_lshlrev_b32_e32 v79, 16, v79
	v_cndmask_b32_e64 v5, 0, 1.0, vcc
	v_fmac_f32_e32 v6, v1, v67
	v_fmac_f32_e32 v4, v1, v74
	v_lshl_add_u64 v[114:115], v[104:105], 0, s[0:1]
	s_mov_b64 s[0:1], 0x1800
	v_mul_f32_e32 v5, v5, v79
	v_fmac_f32_e32 v6, v3, v74
	v_fmac_f32_e32 v4, v3, v75
	v_lshl_add_u64 v[116:117], v[104:105], 0, s[0:1]
	s_mov_b64 s[0:1], 0x1c00
	v_fmac_f32_e32 v6, v2, v75
	v_fmac_f32_e32 v4, v2, v5
	v_cvt_pk_bf16_f32 v0, v6, v4
	v_lshl_add_u64 v[118:119], v[104:105], 0, s[0:1]
	s_mov_b64 s[0:1], 0x2000
	ds_write_b16 v187, v0 offset:8928
	ds_write_b16_d16_hi v187, v0 offset:9072
	v_lshl_add_u64 v[120:121], v[104:105], 0, s[0:1]
	s_mov_b64 s[0:1], 0x2400
	s_waitcnt lgkmcnt(0)
	v_lshl_add_u64 v[122:123], v[104:105], 0, s[0:1]
	s_mov_b64 s[0:1], 0x2800
	ds_read_b128 v[0:3], v211
	ds_read_b128 v[4:7], v211 offset:64
	ds_read_b128 v[8:11], v211 offset:576
	ds_read_b128 v[12:15], v211 offset:640
	ds_read_b128 v[16:19], v211 offset:1152
	ds_read_b128 v[20:23], v211 offset:1216
	ds_read_b128 v[24:27], v211 offset:1728
	ds_read_b128 v[28:31], v211 offset:1792
	v_lshl_add_u64 v[124:125], v[104:105], 0, s[0:1]
	s_mov_b64 s[0:1], 0x2c00
	v_lshl_add_u64 v[126:127], v[104:105], 0, s[0:1]
	s_mov_b64 s[0:1], 0x3000
	v_lshl_add_u64 v[138:139], v[104:105], 0, s[0:1]
	s_mov_b64 s[0:1], 0x3400
	v_lshl_add_u64 v[140:141], v[104:105], 0, s[0:1]
	s_mov_b64 s[0:1], 0x3800
	v_lshl_add_u64 v[142:143], v[104:105], 0, s[0:1]
	s_mov_b64 s[0:1], 0x3c00
	v_lshl_add_u64 v[144:145], v[104:105], 0, s[0:1]
	s_mov_b64 s[0:1], 0x123e2000
	v_lshl_add_u64 v[146:147], v[34:35], 0, s[0:1]
	v_lshl_or_b32 v34, v32, 13, v212
	v_readlane_b32 s0, v253, 38
	v_lshl_add_u64 v[148:149], v[100:101], 0, v[34:35]
	v_add_lshl_u32 v34, v99, v33, 2
	v_readlane_b32 s1, v253, 39
	v_add_u32_e32 v32, v185, v33
	v_lshl_add_u64 v[108:109], v[104:105], 0, s[64:65]
	v_lshl_add_u64 v[150:151], s[0:1], 0, v[34:35]
	v_add_u32_e32 v34, v209, v33
	v_lshl_add_u64 v[152:153], v[34:35], 2, v[134:135]
	v_add_u32_e32 v34, v210, v33
	v_lshl_add_u64 v[154:155], v[34:35], 2, s[0:1]
	v_lshl_or_b32 v102, v32, 2, v102
	s_branch .LBB0_557

; __device__ __forceinline__ int queue_pull(unsigned* q, int lane) { unsigned nx = 0; if (lane == 0) nx = __hip_atomic_fetch_add(q, 1u, __ATOMIC_RELAXED, __HIP_MEMORY_SCOPE_AGENT); return 256 + (int)__builtin_amdgcn_readfirstlane(nx); }
; __device__ __forceinline__ int lru_pass1(const Params& P, int l, LAS unsigned char* lds, unsigned* qw) {
;     ...
;         asm volatile("s_waitcnt lgkmcnt(0)" ::: "memory");
;         local = queue_pull(qw, lane);
.LBB0_625:
	s_waitcnt lgkmcnt(0)
	s_waitcnt vmcnt(0)
	v_mov_b32_e32 v0, v232
	s_mov_b64 s[8:9], 0
	s_branch .LBB0_548
